# v6 + attention-A group-0 merge epilogue: gather loads of all 4 rounds hoisted with counted vmcnt; per-unit store drain before the unit barrier removed
# baseline (speedup 1.0000x reference)
.LBB0_94:
	s_add_i32 s11, s11, s73
	s_cmp_ge_i32 s11, s12
	s_waitcnt lgkmcnt(0)
	s_barrier
	s_cbranch_scc1 .LBB0_115

.LBB0_113:
	s_andn2_b64 vcc, exec, s[6:7]
	s_cbranch_vccnz .LBB0_94
	v_or_b32_e32 v1, s26, v144
	v_ashrrev_i32_e32 v2, 2, v132
	v_add_u32_e32 v10, v1, v2
	v_or_b32_e32 v1, s26, v145
	v_ashrrev_i32_e32 v2, 4, v132
	v_cmp_gt_f32_e32 vcc, s65, v133
	v_add_u32_e32 v12, v1, v2
	v_ashrrev_i32_e32 v11, 31, v10
	v_cndmask_b32_e64 v2, 0, 32, vcc
	v_ldexp_f32 v2, v133, v2
	v_log_f32_e32 v2, v2
	v_cndmask_b32_e32 v1, 0, v225, vcc
	s_lshl_b32 s16, s25, 2
	v_ashrrev_i32_e32 v13, 31, v12
	v_sub_f32_e32 v1, v2, v1
	v_lshlrev_b64 v[2:3], 6, v[10:11]
	v_lshl_add_u64 v[2:3], s[78:79], 0, v[2:3]
	v_lshl_add_u64 v[2:3], v[2:3], 0, s[16:17]
	v_add_co_u32_e32 v2, vcc, s31, v2
	v_add_f32_e32 v1, v146, v1
	s_nop 0
	v_addc_co_u32_e32 v3, vcc, 0, v3, vcc
	global_load_dword v4, v[2:3], off
	v_lshlrev_b64 v[2:3], 6, v[12:13]
	v_lshl_add_u64 v[2:3], s[78:79], 0, v[2:3]
	v_lshl_add_u64 v[2:3], v[2:3], 0, s[16:17]
	v_add_co_u32_e32 v2, vcc, s8, v2
	v_lshlrev_b64 v[10:11], 12, v[10:11]
	s_nop 0
	v_addc_co_u32_e32 v3, vcc, 0, v3, vcc
	global_load_dword v2, v[2:3], off
	v_lshl_add_u64 v[10:11], s[40:41], 0, v[10:11]
	s_lshl_b32 s16, s24, 1
	v_lshlrev_b64 v[12:13], 12, v[12:13]
	v_lshl_add_u64 v[10:11], v[10:11], 0, s[16:17]
	v_lshl_add_u64 v[14:15], s[38:39], 0, v[14:15]
	v_lshl_add_u64 v[14:15], v[14:15], 0, s[16:17]
	s_waitcnt vmcnt(0)
	v_max3_f32 v3, v1, v4, v2
	v_sub_f32_e32 v1, v1, v3
	v_cmp_gt_f32_e32 vcc, s9, v1
	v_sub_f32_e32 v4, v4, v3
	v_sub_f32_e32 v2, v2, v3
	v_cndmask_b32_e32 v5, 0, v222, vcc
	v_add_f32_e32 v1, v1, v5
	v_exp_f32_e32 v1, v1
	v_cndmask_b32_e32 v5, 0, v224, vcc
	v_cmp_gt_f32_e32 vcc, s9, v4
	v_ldexp_f32 v1, v1, v5
	s_nop 0
	v_cndmask_b32_e32 v5, 0, v222, vcc
	v_add_f32_e32 v4, v4, v5
	v_cndmask_b32_e32 v5, 0, v224, vcc
	v_cmp_gt_f32_e32 vcc, s9, v2
	v_exp_f32_e32 v4, v4
	s_nop 0
	v_cndmask_b32_e32 v3, 0, v222, vcc
	v_add_f32_e32 v2, v2, v3
	v_exp_f32_e32 v2, v2
	v_ldexp_f32 v5, v4, v5
	v_cndmask_b32_e32 v3, 0, v224, vcc
	v_ldexp_f32 v2, v2, v3
	v_add_f32_e32 v3, v1, v5
	v_add_f32_e32 v3, v2, v3
	v_div_scale_f32 v4, s[0:1], v3, v3, 1.0
	v_rcp_f32_e32 v6, v4
	s_nop 0
	v_fma_f32 v7, -v4, v6, 1.0
	v_fmac_f32_e32 v6, v7, v6
	v_div_scale_f32 v7, vcc, 1.0, v3, 1.0
	v_mul_f32_e32 v9, v7, v6
	v_fma_f32 v80, -v4, v9, v7
	v_fmac_f32_e32 v9, v80, v6
	v_fma_f32 v4, -v4, v9, v7
	v_div_fmas_f32 v4, v4, v6, v9
	v_div_fixup_f32 v3, v4, v3, 1.0
	v_div_scale_f32 v4, s[0:1], v133, v133, v3
	v_rcp_f32_e32 v6, v4
	v_readlane_b32 s0, v252, 23
	v_readlane_b32 s1, v252, 24
	v_mul_f32_e32 v2, v2, v3
	v_fma_f32 v7, -v4, v6, 1.0
	v_fmac_f32_e32 v6, v7, v6
	v_div_scale_f32 v7, vcc, v3, v133, v3
	v_mul_f32_e32 v9, v7, v6
	v_fma_f32 v80, -v4, v9, v7
	v_fmac_f32_e32 v9, v80, v6
	v_fma_f32 v4, -v4, v9, v7
	v_div_fmas_f32 v4, v4, v6, v9
	v_mov_b32_e32 v9, v0
	v_lshl_add_u64 v[12:13], s[0:1], 0, v[12:13]
	v_lshl_add_u64 v[10:11], v[10:11], 0, v[8:9]
	v_lshl_add_u64 v[12:13], v[12:13], 0, s[16:17]
	v_lshl_add_u64 v[12:13], v[12:13], 0, v[8:9]
	v_lshl_add_u64 v[8:9], v[14:15], 0, v[8:9]
	global_load_dwordx2 v[90:91], v[10:11], off
	global_load_dwordx2 v[92:93], v[12:13], off
	global_load_dwordx2 v[84:85], v[10:11], off offset:16
	global_load_dwordx2 v[82:83], v[12:13], off offset:16
	global_load_dwordx2 v[88:89], v[10:11], off offset:32
	global_load_dwordx2 v[86:87], v[12:13], off offset:32
	global_load_dwordx2 v[80:81], v[10:11], off offset:48
	global_load_dwordx2 v[14:15], v[12:13], off offset:48
	global_load_dwordx2 v[152:153], v[10:11], off offset:64
	global_load_dwordx2 v[154:155], v[12:13], off offset:64
	global_load_dwordx2 v[156:157], v[10:11], off offset:80
	global_load_dwordx2 v[158:159], v[12:13], off offset:80
	global_load_dwordx2 v[160:161], v[10:11], off offset:96
	global_load_dwordx2 v[162:163], v[12:13], off offset:96
	global_load_dwordx2 v[164:165], v[10:11], off offset:112
	global_load_dwordx2 v[166:167], v[12:13], off offset:112
	global_load_dwordx2 v[168:169], v[10:11], off offset:128
	global_load_dwordx2 v[170:171], v[12:13], off offset:128
	global_load_dwordx2 v[172:173], v[10:11], off offset:144
	global_load_dwordx2 v[174:175], v[12:13], off offset:144
	global_load_dwordx2 v[176:177], v[10:11], off offset:160
	global_load_dwordx2 v[178:179], v[12:13], off offset:160
	global_load_dwordx2 v[180:181], v[10:11], off offset:176
	global_load_dwordx2 v[182:183], v[12:13], off offset:176
	global_load_dwordx2 v[184:185], v[10:11], off offset:192
	global_load_dwordx2 v[186:187], v[12:13], off offset:192
	global_load_dwordx2 v[188:189], v[10:11], off offset:208
	global_load_dwordx2 v[190:191], v[12:13], off offset:208
	global_load_dwordx2 v[192:193], v[10:11], off offset:224
	global_load_dwordx2 v[194:195], v[12:13], off offset:224
	global_load_dwordx2 v[196:197], v[10:11], off offset:240
	global_load_dwordx2 v[198:199], v[12:13], off offset:240
	v_div_fixup_f32 v4, v4, v133, v3
	v_mul_f32_e32 v4, v1, v4
	v_mul_f32_e32 v6, v5, v3
	v_pk_mul_f32 v[64:65], v[64:65], v[4:5] op_sel_hi:[1,0]
	v_pk_mul_f32 v[66:67], v[66:67], v[4:5] op_sel_hi:[1,0]
	s_waitcnt vmcnt(24)
	v_lshlrev_b32_e32 v94, 16, v90
	v_and_b32_e32 v95, 0xffff0000, v90
	v_lshlrev_b32_e32 v90, 16, v91
	v_and_b32_e32 v91, 0xffff0000, v91
	v_pk_fma_f32 v[64:65], v[6:7], v[94:95], v[64:65] op_sel_hi:[0,1,1]
	v_lshlrev_b32_e32 v94, 16, v92
	v_and_b32_e32 v95, 0xffff0000, v92
	v_pk_fma_f32 v[66:67], v[6:7], v[90:91], v[66:67] op_sel_hi:[0,1,1]
	v_lshlrev_b32_e32 v90, 16, v93
	v_and_b32_e32 v91, 0xffff0000, v93
	v_pk_fma_f32 v[64:65], v[2:3], v[94:95], v[64:65] op_sel_hi:[0,1,1]
	v_pk_fma_f32 v[66:67], v[2:3], v[90:91], v[66:67] op_sel_hi:[0,1,1]
	v_cvt_pk_bf16_f32 v64, v64, v65
	v_cvt_pk_bf16_f32 v65, v66, v67
	global_store_dwordx2 v[8:9], v[64:65], off
	v_pk_mul_f32 v[64:65], v[68:69], v[4:5] op_sel_hi:[1,0]
	v_lshlrev_b32_e32 v66, 16, v84
	v_and_b32_e32 v67, 0xffff0000, v84
	v_pk_fma_f32 v[64:65], v[6:7], v[66:67], v[64:65] op_sel_hi:[0,1,1]
	v_lshlrev_b32_e32 v66, 16, v82
	v_and_b32_e32 v67, 0xffff0000, v82
	v_pk_fma_f32 v[64:65], v[2:3], v[66:67], v[64:65] op_sel_hi:[0,1,1]
	v_pk_mul_f32 v[66:67], v[70:71], v[4:5] op_sel_hi:[1,0]
	v_lshlrev_b32_e32 v68, 16, v85
	v_and_b32_e32 v69, 0xffff0000, v85
	v_pk_fma_f32 v[66:67], v[6:7], v[68:69], v[66:67] op_sel_hi:[0,1,1]
	v_lshlrev_b32_e32 v68, 16, v83
	v_and_b32_e32 v69, 0xffff0000, v83
	v_pk_fma_f32 v[66:67], v[2:3], v[68:69], v[66:67] op_sel_hi:[0,1,1]
	v_cvt_pk_bf16_f32 v64, v64, v65
	v_cvt_pk_bf16_f32 v65, v66, v67
	global_store_dwordx2 v[8:9], v[64:65], off offset:16
	v_pk_mul_f32 v[64:65], v[72:73], v[4:5] op_sel_hi:[1,0]
	v_lshlrev_b32_e32 v66, 16, v88
	v_and_b32_e32 v67, 0xffff0000, v88
	v_pk_fma_f32 v[64:65], v[6:7], v[66:67], v[64:65] op_sel_hi:[0,1,1]
	v_lshlrev_b32_e32 v66, 16, v86
	v_and_b32_e32 v67, 0xffff0000, v86
	v_pk_fma_f32 v[64:65], v[2:3], v[66:67], v[64:65] op_sel_hi:[0,1,1]
	v_pk_mul_f32 v[66:67], v[74:75], v[4:5] op_sel_hi:[1,0]
	v_lshlrev_b32_e32 v68, 16, v89
	v_and_b32_e32 v69, 0xffff0000, v89
	v_pk_fma_f32 v[66:67], v[6:7], v[68:69], v[66:67] op_sel_hi:[0,1,1]
	v_lshlrev_b32_e32 v68, 16, v87
	v_and_b32_e32 v69, 0xffff0000, v87
	v_pk_fma_f32 v[66:67], v[2:3], v[68:69], v[66:67] op_sel_hi:[0,1,1]
	v_cvt_pk_bf16_f32 v64, v64, v65
	v_cvt_pk_bf16_f32 v65, v66, v67
	global_store_dwordx2 v[8:9], v[64:65], off offset:32
	v_lshlrev_b32_e32 v64, 16, v80
	v_and_b32_e32 v65, 0xffff0000, v80
	v_pk_mul_f32 v[64:65], v[6:7], v[64:65] op_sel_hi:[0,1]
	v_pk_fma_f32 v[64:65], v[76:77], v[4:5], v[64:65] op_sel_hi:[1,0,1]
	v_lshlrev_b32_e32 v66, 16, v14
	v_and_b32_e32 v67, 0xffff0000, v14
	v_pk_fma_f32 v[64:65], v[2:3], v[66:67], v[64:65] op_sel_hi:[0,1,1]
	v_cvt_pk_bf16_f32 v14, v64, v65
	v_lshlrev_b32_e32 v64, 16, v81
	v_and_b32_e32 v65, 0xffff0000, v81
	v_pk_mul_f32 v[64:65], v[6:7], v[64:65] op_sel_hi:[0,1]
	v_pk_fma_f32 v[64:65], v[78:79], v[4:5], v[64:65] op_sel_hi:[1,0,1]
	v_lshlrev_b32_e32 v66, 16, v15
	v_and_b32_e32 v67, 0xffff0000, v15
	v_pk_fma_f32 v[64:65], v[2:3], v[66:67], v[64:65] op_sel_hi:[0,1,1]
	v_cvt_pk_bf16_f32 v15, v64, v65
	global_store_dwordx2 v[8:9], v[14:15], off offset:48
	s_waitcnt vmcnt(20)
	v_lshlrev_b32_e32 v78, 16, v152
	v_and_b32_e32 v79, 0xffff0000, v152
	v_pk_mul_f32 v[78:79], v[6:7], v[78:79] op_sel_hi:[0,1]
	v_pk_fma_f32 v[48:49], v[48:49], v[4:5], v[78:79] op_sel_hi:[1,0,1]
	v_lshlrev_b32_e32 v78, 16, v154
	v_and_b32_e32 v79, 0xffff0000, v154
	v_pk_fma_f32 v[48:49], v[2:3], v[78:79], v[48:49] op_sel_hi:[0,1,1]
	v_cvt_pk_bf16_f32 v14, v48, v49
	v_lshlrev_b32_e32 v48, 16, v153
	v_and_b32_e32 v49, 0xffff0000, v153
	v_pk_mul_f32 v[48:49], v[6:7], v[48:49] op_sel_hi:[0,1]
	v_pk_fma_f32 v[48:49], v[50:51], v[4:5], v[48:49] op_sel_hi:[1,0,1]
	v_lshlrev_b32_e32 v50, 16, v155
	v_and_b32_e32 v51, 0xffff0000, v155
	v_pk_fma_f32 v[48:49], v[2:3], v[50:51], v[48:49] op_sel_hi:[0,1,1]
	v_cvt_pk_bf16_f32 v15, v48, v49
	global_store_dwordx2 v[8:9], v[14:15], off offset:64
	v_lshlrev_b32_e32 v14, 16, v156
	v_and_b32_e32 v15, 0xffff0000, v156
	v_pk_mul_f32 v[14:15], v[6:7], v[14:15] op_sel_hi:[0,1]
	v_pk_fma_f32 v[14:15], v[52:53], v[4:5], v[14:15] op_sel_hi:[1,0,1]
	v_lshlrev_b32_e32 v48, 16, v158
	v_and_b32_e32 v49, 0xffff0000, v158
	v_pk_fma_f32 v[14:15], v[2:3], v[48:49], v[14:15] op_sel_hi:[0,1,1]
	v_lshlrev_b32_e32 v48, 16, v157
	v_and_b32_e32 v49, 0xffff0000, v157
	v_pk_mul_f32 v[48:49], v[6:7], v[48:49] op_sel_hi:[0,1]
	v_pk_fma_f32 v[48:49], v[54:55], v[4:5], v[48:49] op_sel_hi:[1,0,1]
	v_lshlrev_b32_e32 v50, 16, v159
	v_and_b32_e32 v51, 0xffff0000, v159
	v_pk_fma_f32 v[48:49], v[2:3], v[50:51], v[48:49] op_sel_hi:[0,1,1]
	v_cvt_pk_bf16_f32 v14, v14, v15
	v_cvt_pk_bf16_f32 v15, v48, v49
	global_store_dwordx2 v[8:9], v[14:15], off offset:80
	v_lshlrev_b32_e32 v14, 16, v160
	v_and_b32_e32 v15, 0xffff0000, v160
	v_pk_mul_f32 v[14:15], v[6:7], v[14:15] op_sel_hi:[0,1]
	v_pk_fma_f32 v[14:15], v[56:57], v[4:5], v[14:15] op_sel_hi:[1,0,1]
	v_lshlrev_b32_e32 v48, 16, v162
	v_and_b32_e32 v49, 0xffff0000, v162
	v_pk_fma_f32 v[14:15], v[2:3], v[48:49], v[14:15] op_sel_hi:[0,1,1]
	v_lshlrev_b32_e32 v48, 16, v161
	v_and_b32_e32 v49, 0xffff0000, v161
	v_pk_mul_f32 v[48:49], v[6:7], v[48:49] op_sel_hi:[0,1]
	v_pk_fma_f32 v[48:49], v[58:59], v[4:5], v[48:49] op_sel_hi:[1,0,1]
	v_lshlrev_b32_e32 v50, 16, v163
	v_and_b32_e32 v51, 0xffff0000, v163
	v_pk_fma_f32 v[48:49], v[2:3], v[50:51], v[48:49] op_sel_hi:[0,1,1]
	v_cvt_pk_bf16_f32 v14, v14, v15
	v_cvt_pk_bf16_f32 v15, v48, v49
	global_store_dwordx2 v[8:9], v[14:15], off offset:96
	v_lshlrev_b32_e32 v14, 16, v164
	v_and_b32_e32 v15, 0xffff0000, v164
	v_pk_mul_f32 v[14:15], v[6:7], v[14:15] op_sel_hi:[0,1]
	v_pk_fma_f32 v[14:15], v[60:61], v[4:5], v[14:15] op_sel_hi:[1,0,1]
	v_lshlrev_b32_e32 v48, 16, v166
	v_and_b32_e32 v49, 0xffff0000, v166
	v_pk_fma_f32 v[14:15], v[2:3], v[48:49], v[14:15] op_sel_hi:[0,1,1]
	v_lshlrev_b32_e32 v48, 16, v165
	v_and_b32_e32 v49, 0xffff0000, v165
	v_pk_mul_f32 v[48:49], v[6:7], v[48:49] op_sel_hi:[0,1]
	v_pk_fma_f32 v[48:49], v[62:63], v[4:5], v[48:49] op_sel_hi:[1,0,1]
	v_lshlrev_b32_e32 v50, 16, v167
	v_and_b32_e32 v51, 0xffff0000, v167
	v_pk_fma_f32 v[48:49], v[2:3], v[50:51], v[48:49] op_sel_hi:[0,1,1]
	v_cvt_pk_bf16_f32 v14, v14, v15
	v_cvt_pk_bf16_f32 v15, v48, v49
	global_store_dwordx2 v[8:9], v[14:15], off offset:112
	s_waitcnt vmcnt(16)
	v_lshlrev_b32_e32 v62, 16, v168
	v_and_b32_e32 v63, 0xffff0000, v168
	v_lshlrev_b32_e32 v50, 16, v169
	v_and_b32_e32 v51, 0xffff0000, v169
	v_pk_mul_f32 v[62:63], v[6:7], v[62:63] op_sel_hi:[0,1]
	v_pk_mul_f32 v[50:51], v[6:7], v[50:51] op_sel_hi:[0,1]
	v_pk_fma_f32 v[32:33], v[32:33], v[4:5], v[62:63] op_sel_hi:[1,0,1]
	v_lshlrev_b32_e32 v62, 16, v170
	v_and_b32_e32 v63, 0xffff0000, v170
	v_pk_fma_f32 v[34:35], v[34:35], v[4:5], v[50:51] op_sel_hi:[1,0,1]
	v_lshlrev_b32_e32 v50, 16, v171
	v_and_b32_e32 v51, 0xffff0000, v171
	v_pk_fma_f32 v[32:33], v[2:3], v[62:63], v[32:33] op_sel_hi:[0,1,1]
	v_pk_fma_f32 v[34:35], v[2:3], v[50:51], v[34:35] op_sel_hi:[0,1,1]
	v_cvt_pk_bf16_f32 v32, v32, v33
	v_cvt_pk_bf16_f32 v33, v34, v35
	global_store_dwordx2 v[8:9], v[32:33], off offset:128
	v_lshlrev_b32_e32 v32, 16, v172
	v_and_b32_e32 v33, 0xffff0000, v172
	v_pk_mul_f32 v[32:33], v[6:7], v[32:33] op_sel_hi:[0,1]
	v_pk_fma_f32 v[32:33], v[36:37], v[4:5], v[32:33] op_sel_hi:[1,0,1]
	v_lshlrev_b32_e32 v34, 16, v174
	v_and_b32_e32 v35, 0xffff0000, v174
	v_pk_fma_f32 v[32:33], v[2:3], v[34:35], v[32:33] op_sel_hi:[0,1,1]
	v_lshlrev_b32_e32 v34, 16, v173
	v_and_b32_e32 v35, 0xffff0000, v173
	v_pk_mul_f32 v[34:35], v[6:7], v[34:35] op_sel_hi:[0,1]
	v_pk_fma_f32 v[34:35], v[38:39], v[4:5], v[34:35] op_sel_hi:[1,0,1]
	v_lshlrev_b32_e32 v36, 16, v175
	v_and_b32_e32 v37, 0xffff0000, v175
	v_pk_fma_f32 v[34:35], v[2:3], v[36:37], v[34:35] op_sel_hi:[0,1,1]
	v_cvt_pk_bf16_f32 v32, v32, v33
	v_cvt_pk_bf16_f32 v33, v34, v35
	global_store_dwordx2 v[8:9], v[32:33], off offset:144
	v_lshlrev_b32_e32 v32, 16, v176
	v_and_b32_e32 v33, 0xffff0000, v176
	v_pk_mul_f32 v[32:33], v[6:7], v[32:33] op_sel_hi:[0,1]
	v_pk_fma_f32 v[32:33], v[40:41], v[4:5], v[32:33] op_sel_hi:[1,0,1]
	v_lshlrev_b32_e32 v34, 16, v178
	v_and_b32_e32 v35, 0xffff0000, v178
	v_pk_fma_f32 v[32:33], v[2:3], v[34:35], v[32:33] op_sel_hi:[0,1,1]
	v_lshlrev_b32_e32 v34, 16, v177
	v_and_b32_e32 v35, 0xffff0000, v177
	v_pk_mul_f32 v[34:35], v[6:7], v[34:35] op_sel_hi:[0,1]
	v_pk_fma_f32 v[34:35], v[42:43], v[4:5], v[34:35] op_sel_hi:[1,0,1]
	v_lshlrev_b32_e32 v36, 16, v179
	v_and_b32_e32 v37, 0xffff0000, v179
	v_pk_fma_f32 v[34:35], v[2:3], v[36:37], v[34:35] op_sel_hi:[0,1,1]
	v_cvt_pk_bf16_f32 v32, v32, v33
	v_cvt_pk_bf16_f32 v33, v34, v35
	global_store_dwordx2 v[8:9], v[32:33], off offset:160
	v_lshlrev_b32_e32 v32, 16, v180
	v_and_b32_e32 v33, 0xffff0000, v180
	v_pk_mul_f32 v[32:33], v[6:7], v[32:33] op_sel_hi:[0,1]
	v_pk_fma_f32 v[32:33], v[44:45], v[4:5], v[32:33] op_sel_hi:[1,0,1]
	v_lshlrev_b32_e32 v34, 16, v182
	v_and_b32_e32 v35, 0xffff0000, v182
	v_pk_fma_f32 v[32:33], v[2:3], v[34:35], v[32:33] op_sel_hi:[0,1,1]
	v_cvt_pk_bf16_f32 v14, v32, v33
	v_lshlrev_b32_e32 v32, 16, v181
	v_and_b32_e32 v33, 0xffff0000, v181
	v_pk_mul_f32 v[32:33], v[6:7], v[32:33] op_sel_hi:[0,1]
	v_pk_fma_f32 v[32:33], v[46:47], v[4:5], v[32:33] op_sel_hi:[1,0,1]
	v_lshlrev_b32_e32 v34, 16, v183
	v_and_b32_e32 v35, 0xffff0000, v183
	v_pk_fma_f32 v[32:33], v[2:3], v[34:35], v[32:33] op_sel_hi:[0,1,1]
	v_cvt_pk_bf16_f32 v15, v32, v33
	global_store_dwordx2 v[8:9], v[14:15], off offset:176
	s_nop 0
	s_waitcnt vmcnt(12)
	v_lshlrev_b32_e32 v12, 16, v184
	v_and_b32_e32 v13, 0xffff0000, v184
	v_pk_mul_f32 v[12:13], v[6:7], v[12:13] op_sel_hi:[0,1]
	v_pk_fma_f32 v[12:13], v[16:17], v[4:5], v[12:13] op_sel_hi:[1,0,1]
	v_lshlrev_b32_e32 v16, 16, v186
	v_and_b32_e32 v17, 0xffff0000, v186
	v_pk_fma_f32 v[12:13], v[2:3], v[16:17], v[12:13] op_sel_hi:[0,1,1]
	v_lshlrev_b32_e32 v16, 16, v185
	v_and_b32_e32 v17, 0xffff0000, v185
	v_pk_mul_f32 v[16:17], v[6:7], v[16:17] op_sel_hi:[0,1]
	v_pk_fma_f32 v[16:17], v[18:19], v[4:5], v[16:17] op_sel_hi:[1,0,1]
	v_lshlrev_b32_e32 v18, 16, v187
	v_and_b32_e32 v19, 0xffff0000, v187
	v_pk_fma_f32 v[16:17], v[2:3], v[18:19], v[16:17] op_sel_hi:[0,1,1]
	v_cvt_pk_bf16_f32 v12, v12, v13
	v_cvt_pk_bf16_f32 v13, v16, v17
	global_store_dwordx2 v[8:9], v[12:13], off offset:192
	v_lshlrev_b32_e32 v12, 16, v188
	v_and_b32_e32 v13, 0xffff0000, v188
	v_pk_mul_f32 v[12:13], v[6:7], v[12:13] op_sel_hi:[0,1]
	v_pk_fma_f32 v[12:13], v[20:21], v[4:5], v[12:13] op_sel_hi:[1,0,1]
	v_lshlrev_b32_e32 v16, 16, v190
	v_and_b32_e32 v17, 0xffff0000, v190
	v_pk_fma_f32 v[12:13], v[2:3], v[16:17], v[12:13] op_sel_hi:[0,1,1]
	v_lshlrev_b32_e32 v16, 16, v189
	v_and_b32_e32 v17, 0xffff0000, v189
	v_pk_mul_f32 v[16:17], v[6:7], v[16:17] op_sel_hi:[0,1]
	v_pk_fma_f32 v[16:17], v[22:23], v[4:5], v[16:17] op_sel_hi:[1,0,1]
	v_lshlrev_b32_e32 v18, 16, v191
	v_and_b32_e32 v19, 0xffff0000, v191
	v_pk_fma_f32 v[16:17], v[2:3], v[18:19], v[16:17] op_sel_hi:[0,1,1]
	v_cvt_pk_bf16_f32 v12, v12, v13
	v_cvt_pk_bf16_f32 v13, v16, v17
	global_store_dwordx2 v[8:9], v[12:13], off offset:208
	v_lshlrev_b32_e32 v12, 16, v192
	v_and_b32_e32 v13, 0xffff0000, v192
	v_pk_mul_f32 v[12:13], v[6:7], v[12:13] op_sel_hi:[0,1]
	v_pk_fma_f32 v[12:13], v[24:25], v[4:5], v[12:13] op_sel_hi:[1,0,1]
	v_lshlrev_b32_e32 v16, 16, v194
	v_and_b32_e32 v17, 0xffff0000, v194
	v_pk_fma_f32 v[12:13], v[2:3], v[16:17], v[12:13] op_sel_hi:[0,1,1]
	v_lshlrev_b32_e32 v16, 16, v193
	v_and_b32_e32 v17, 0xffff0000, v193
	v_pk_mul_f32 v[16:17], v[6:7], v[16:17] op_sel_hi:[0,1]
	v_pk_fma_f32 v[16:17], v[26:27], v[4:5], v[16:17] op_sel_hi:[1,0,1]
	v_lshlrev_b32_e32 v18, 16, v195
	v_and_b32_e32 v19, 0xffff0000, v195
	v_pk_fma_f32 v[16:17], v[2:3], v[18:19], v[16:17] op_sel_hi:[0,1,1]
	v_cvt_pk_bf16_f32 v12, v12, v13
	v_cvt_pk_bf16_f32 v13, v16, v17
	global_store_dwordx2 v[8:9], v[12:13], off offset:224
	v_lshlrev_b32_e32 v12, 16, v196
	v_and_b32_e32 v13, 0xffff0000, v196
	v_pk_mul_f32 v[12:13], v[6:7], v[12:13] op_sel_hi:[0,1]
	v_pk_fma_f32 v[12:13], v[28:29], v[4:5], v[12:13] op_sel_hi:[1,0,1]
	v_lshlrev_b32_e32 v16, 16, v198
	v_and_b32_e32 v17, 0xffff0000, v198
	v_pk_fma_f32 v[12:13], v[2:3], v[16:17], v[12:13] op_sel_hi:[0,1,1]
	v_cvt_pk_bf16_f32 v10, v12, v13
	v_lshlrev_b32_e32 v12, 16, v197
	v_and_b32_e32 v13, 0xffff0000, v197
	v_pk_mul_f32 v[6:7], v[6:7], v[12:13] op_sel_hi:[0,1]
	v_pk_fma_f32 v[4:5], v[30:31], v[4:5], v[6:7] op_sel_hi:[1,0,1]
	v_lshlrev_b32_e32 v6, 16, v199
	v_and_b32_e32 v7, 0xffff0000, v199
	v_pk_fma_f32 v[2:3], v[2:3], v[6:7], v[4:5] op_sel_hi:[0,1,1]
	v_cvt_pk_bf16_f32 v11, v2, v3
	global_store_dwordx2 v[8:9], v[10:11], off offset:240
	s_branch .LBB0_94
